# GEMM accumulator clearing with v_mov_b64 in all nine GEMM tile loops (gate GEMM block included)
# speedup vs baseline: 1.0179x; 1.0018x over previous
; template <class Epi, class S_t>
; __device__ __forceinline__ void gemm_phase(LAS unsigned char* lds, int lda, int ldb, const S_t& S, const Epi& E) {
;     ...
; #pragma unroll
;         for (int a = 0; a < 2; ++a)
; #pragma unroll
;             for (int b = 0; b < 2; ++b)
; #pragma unroll
;                 for (int m = 0; m < 4; ++m)
; #pragma unroll
;                     for (int n = 0; n < 2; ++n) acc[a][b][m][n] = (f32x4){0.f, 0.f, 0.f, 0.f};
;         cur = nxt; cA = nA; cB = nB; ++ui;
.LBB0_546:
	s_mov_b32 s0, 0
	s_mov_b64 s[66:67], -1
	s_mov_b64 s[68:69], 0
	v_mov_b64_e32 v[0:1], 0
	v_mov_b64_e32 v[2:3], 0
	v_mov_b64_e32 v[4:5], 0
	v_mov_b64_e32 v[6:7], 0
	v_mov_b64_e32 v[8:9], 0
	v_mov_b64_e32 v[10:11], 0
	v_mov_b64_e32 v[12:13], 0
	v_mov_b64_e32 v[14:15], 0
	v_mov_b64_e32 v[16:17], 0
	v_mov_b64_e32 v[18:19], 0
	v_mov_b64_e32 v[20:21], 0
	v_mov_b64_e32 v[22:23], 0
	v_mov_b64_e32 v[24:25], 0
	v_mov_b64_e32 v[26:27], 0
	v_mov_b64_e32 v[28:29], 0
	v_mov_b64_e32 v[30:31], 0
	v_mov_b64_e32 v[40:41], 0
	v_mov_b64_e32 v[42:43], 0
	v_mov_b64_e32 v[44:45], 0
	v_mov_b64_e32 v[46:47], 0
	v_mov_b64_e32 v[60:61], 0
	v_mov_b64_e32 v[62:63], 0
	v_mov_b64_e32 v[72:73], 0
	v_mov_b64_e32 v[74:75], 0
	v_mov_b64_e32 v[80:81], 0
	v_mov_b64_e32 v[82:83], 0
	v_mov_b64_e32 v[84:85], 0
	v_mov_b64_e32 v[86:87], 0
	v_mov_b64_e32 v[88:89], 0
	v_mov_b64_e32 v[90:91], 0
	v_mov_b64_e32 v[92:93], 0
	v_mov_b64_e32 v[94:95], 0
	v_mov_b64_e32 v[100:101], 0
	v_mov_b64_e32 v[102:103], 0
	v_mov_b64_e32 v[104:105], 0
	v_mov_b64_e32 v[106:107], 0
	v_mov_b64_e32 v[108:109], 0
	v_mov_b64_e32 v[110:111], 0
	v_mov_b64_e32 v[112:113], 0
	v_mov_b64_e32 v[114:115], 0
	v_mov_b64_e32 v[120:121], 0
	v_mov_b64_e32 v[122:123], 0
	v_mov_b64_e32 v[124:125], 0
	v_mov_b64_e32 v[126:127], 0
	v_mov_b64_e32 v[128:129], 0
	v_mov_b64_e32 v[130:131], 0
	v_mov_b64_e32 v[132:133], 0
	v_mov_b64_e32 v[134:135], 0
	v_mov_b64_e32 v[140:141], 0
	v_mov_b64_e32 v[142:143], 0
	v_mov_b64_e32 v[144:145], 0
	v_mov_b64_e32 v[146:147], 0
	v_mov_b64_e32 v[148:149], 0
	v_mov_b64_e32 v[150:151], 0
	v_mov_b64_e32 v[152:153], 0
	v_mov_b64_e32 v[154:155], 0
	v_mov_b64_e32 v[160:161], 0
	v_mov_b64_e32 v[162:163], 0
	v_mov_b64_e32 v[164:165], 0
	v_mov_b64_e32 v[166:167], 0
	v_mov_b64_e32 v[168:169], 0
	v_mov_b64_e32 v[170:171], 0
	v_mov_b64_e32 v[172:173], 0
	v_mov_b64_e32 v[174:175], 0
